# attention exp/PV block rescheduled: all exps first, then PV MFMAs separated by the row-sum adds and bf16 packs (variant chosen by in-kernel microbenchmarks)
# speedup vs baseline: 1.0139x; 1.0037x over previous
; DI unsigned pk2s(float lo, float hi) { f32x2_t v = {lo, hi}; bf16x2_t q = __builtin_convertvector(v, bf16x2_t); return __builtin_bit_cast(unsigned, q); }
; #define MFMA32(a, b, c) __builtin_amdgcn_mfma_f32_32x32x16_bf16((a), (b), (c), 0, 0, 0)
; DI void attn_unit(const bf16_t* Qb, const bf16_t* Kb, const bf16_t* Vt, bf16_t* MIX, int b, int h, int qb, char* lds, int tid_in) {
;     ...
;             float rs = 0.f;
; #pragma unroll
;             for (int kb = 0; kb < 4; ++kb)
; #pragma unroll
;                 for (int i = 0; i < 16; ++i) { const float e = __builtin_amdgcn_exp2f(p[kb][i]); p[kb][i] = e; rs += e; }
;             l_run += rs;
;             {
;                 bf16x8 vf[2][2];
;                 vf[0][0] = *(const bf16x8*)(vb_ + r * AV_PITCH + (8 * hh) * 2); vf[0][1] = *(const bf16x8*)(vb_ + (32 + r) * AV_PITCH + (8 * hh) * 2);
; #pragma unroll
;                 for (int G = 0; G < 8; ++G) { const int kb = G >> 1, s2 = G & 1;
;                     if (G + 1 < 8) { vf[(G + 1) & 1][0] = *(const bf16x8*)(vb_ + r * AV_PITCH + (16 * (G + 1) + 8 * hh) * 2); vf[(G + 1) & 1][1] = *(const bf16x8*)(vb_ + (32 + r) * AV_PITCH + (16 * (G + 1) + 8 * hh) * 2); }
;                     u32x4 pw; pw.x = pk2s(p[kb][8 * s2], p[kb][8 * s2 + 1]); pw.y = pk2s(p[kb][8 * s2 + 2], p[kb][8 * s2 + 3]); pw.z = pk2s(p[kb][8 * s2 + 4], p[kb][8 * s2 + 5]); pw.w = pk2s(p[kb][8 * s2 + 6], p[kb][8 * s2 + 7]);
;                     const bf16x8 pa = __builtin_bit_cast(bf16x8, pw);
;                     __builtin_amdgcn_sched_barrier(0);
;                     __builtin_amdgcn_s_setprio(1);
;                     o0 = MFMA32(pa, vf[G & 1][0], o0); o1 = MFMA32(pa, vf[G & 1][1], o1);
;                     __builtin_amdgcn_s_setprio(0);
;                     __builtin_amdgcn_sched_barrier(0);
;                 }
.LBB0_467:
	v_add3_u32 v244, s16, v175, v176
	ds_read_b128 v[190:193], v244 offset:24576
	ds_read_b128 v[194:197], v244 offset:33280
	ds_read_b128 v[198:201], v244 offset:24608
	ds_read_b128 v[212:215], v244 offset:33312
	v_exp_f32_e32 v82, v82
	v_exp_f32_e32 v83, v83
	v_exp_f32_e32 v84, v84
	v_exp_f32_e32 v85, v85
	v_exp_f32_e32 v86, v86
	v_exp_f32_e32 v87, v87
	v_exp_f32_e32 v88, v88
	v_exp_f32_e32 v89, v89
	v_exp_f32_e32 v90, v90
	v_exp_f32_e32 v91, v91
	v_exp_f32_e32 v92, v92
	v_exp_f32_e32 v93, v93
	v_exp_f32_e32 v94, v94
	v_exp_f32_e32 v95, v95
	v_exp_f32_e32 v96, v96
	v_exp_f32_e32 v97, v97
	v_exp_f32_e32 v66, v66
	v_exp_f32_e32 v67, v67
	v_exp_f32_e32 v68, v68
	v_exp_f32_e32 v69, v69
	v_exp_f32_e32 v70, v70
	v_exp_f32_e32 v71, v71
	v_exp_f32_e32 v72, v72
	v_exp_f32_e32 v73, v73
	v_exp_f32_e32 v74, v74
	v_exp_f32_e32 v75, v75
	v_exp_f32_e32 v76, v76
	v_exp_f32_e32 v77, v77
	v_exp_f32_e32 v78, v78
	v_exp_f32_e32 v79, v79
	v_exp_f32_e32 v80, v80
	v_exp_f32_e32 v81, v81
	v_exp_f32_e32 v50, v50
	v_exp_f32_e32 v51, v51
	v_exp_f32_e32 v52, v52
	v_exp_f32_e32 v53, v53
	v_exp_f32_e32 v54, v54
	v_exp_f32_e32 v55, v55
	v_exp_f32_e32 v56, v56
	v_exp_f32_e32 v57, v57
	v_exp_f32_e32 v58, v58
	v_exp_f32_e32 v59, v59
	v_exp_f32_e32 v60, v60
	v_exp_f32_e32 v61, v61
	v_exp_f32_e32 v62, v62
	v_exp_f32_e32 v63, v63
	v_exp_f32_e32 v64, v64
	v_exp_f32_e32 v65, v65
	v_exp_f32_e32 v34, v34
	v_exp_f32_e32 v35, v35
	v_exp_f32_e32 v36, v36
	v_exp_f32_e32 v37, v37
	v_exp_f32_e32 v38, v38
	v_exp_f32_e32 v39, v39
	v_exp_f32_e32 v40, v40
	v_exp_f32_e32 v41, v41
	v_exp_f32_e32 v42, v42
	v_exp_f32_e32 v43, v43
	v_exp_f32_e32 v44, v44
	v_exp_f32_e32 v45, v45
	v_exp_f32_e32 v46, v46
	v_exp_f32_e32 v47, v47
	v_exp_f32_e32 v48, v48
	v_exp_f32_e32 v49, v49
	v_cvt_pk_bf16_f32 v216, v82, v83
	v_cvt_pk_bf16_f32 v217, v84, v85
	v_cvt_pk_bf16_f32 v218, v86, v87
	v_cvt_pk_bf16_f32 v219, v88, v89
	s_waitcnt lgkmcnt(2)
	s_nop 0
	v_mfma_f32_32x32x16_bf16 v[18:33], v[216:219], v[190:193], v[18:33]
	v_mov_b32_e32 v245, v82
	v_mov_b32_e32 v246, v83
	v_mov_b32_e32 v247, v84
	v_mov_b32_e32 v248, v85
	v_mfma_f32_32x32x16_bf16 v[2:17], v[216:219], v[194:197], v[2:17]
	ds_read_b128 v[190:193], v244 offset:24640
	ds_read_b128 v[194:197], v244 offset:33344
	v_add_f32_e32 v245, v86, v245
	v_add_f32_e32 v246, v87, v246
	v_add_f32_e32 v247, v88, v247
	v_add_f32_e32 v248, v89, v248
	v_cvt_pk_bf16_f32 v224, v90, v91
	v_cvt_pk_bf16_f32 v225, v92, v93
	v_cvt_pk_bf16_f32 v226, v94, v95
	v_cvt_pk_bf16_f32 v227, v96, v97
	s_waitcnt lgkmcnt(2)
	s_nop 0
	v_mfma_f32_32x32x16_bf16 v[18:33], v[224:227], v[198:201], v[18:33]
	v_add_f32_e32 v245, v90, v245
	v_add_f32_e32 v246, v91, v246
	v_add_f32_e32 v247, v92, v247
	v_add_f32_e32 v248, v93, v248
	v_mfma_f32_32x32x16_bf16 v[2:17], v[224:227], v[212:215], v[2:17]
	ds_read_b128 v[198:201], v244 offset:24672
	ds_read_b128 v[212:215], v244 offset:33376
	v_add_f32_e32 v245, v94, v245
	v_add_f32_e32 v246, v95, v246
	v_add_f32_e32 v247, v96, v247
	v_add_f32_e32 v248, v97, v248
	v_cvt_pk_bf16_f32 v216, v66, v67
	v_cvt_pk_bf16_f32 v217, v68, v69
	v_cvt_pk_bf16_f32 v218, v70, v71
	v_cvt_pk_bf16_f32 v219, v72, v73
	s_waitcnt lgkmcnt(2)
	s_nop 0
	v_mfma_f32_32x32x16_bf16 v[18:33], v[216:219], v[190:193], v[18:33]
	v_add_f32_e32 v245, v66, v245
	v_add_f32_e32 v246, v67, v246
	v_add_f32_e32 v247, v68, v247
	v_add_f32_e32 v248, v69, v248
	v_mfma_f32_32x32x16_bf16 v[2:17], v[216:219], v[194:197], v[2:17]
	ds_read_b128 v[190:193], v244 offset:24704
	ds_read_b128 v[194:197], v244 offset:33408
	v_add_f32_e32 v245, v70, v245
	v_add_f32_e32 v246, v71, v246
	v_add_f32_e32 v247, v72, v247
	v_add_f32_e32 v248, v73, v248
	v_cvt_pk_bf16_f32 v224, v74, v75
	v_cvt_pk_bf16_f32 v225, v76, v77
	v_cvt_pk_bf16_f32 v226, v78, v79
	v_cvt_pk_bf16_f32 v227, v80, v81
	s_waitcnt lgkmcnt(2)
	s_nop 0
	v_mfma_f32_32x32x16_bf16 v[18:33], v[224:227], v[198:201], v[18:33]
	v_add_f32_e32 v245, v74, v245
	v_add_f32_e32 v246, v75, v246
	v_add_f32_e32 v247, v76, v247
	v_add_f32_e32 v248, v77, v248
	v_mfma_f32_32x32x16_bf16 v[2:17], v[224:227], v[212:215], v[2:17]
	ds_read_b128 v[198:201], v244 offset:24736
	ds_read_b128 v[212:215], v244 offset:33440
	v_add_f32_e32 v245, v78, v245
	v_add_f32_e32 v246, v79, v246
	v_add_f32_e32 v247, v80, v247
	v_add_f32_e32 v248, v81, v248
	v_cvt_pk_bf16_f32 v216, v50, v51
	v_cvt_pk_bf16_f32 v217, v52, v53
	v_cvt_pk_bf16_f32 v218, v54, v55
	v_cvt_pk_bf16_f32 v219, v56, v57
	s_waitcnt lgkmcnt(2)
	s_nop 0
	v_mfma_f32_32x32x16_bf16 v[18:33], v[216:219], v[190:193], v[18:33]
	v_add_f32_e32 v245, v50, v245
	v_add_f32_e32 v246, v51, v246
	v_add_f32_e32 v247, v52, v247
	v_add_f32_e32 v248, v53, v248
	v_mfma_f32_32x32x16_bf16 v[2:17], v[216:219], v[194:197], v[2:17]
	ds_read_b128 v[190:193], v244 offset:24768
	ds_read_b128 v[194:197], v244 offset:33472
	v_add_f32_e32 v245, v54, v245
	v_add_f32_e32 v246, v55, v246
	v_add_f32_e32 v247, v56, v247
	v_add_f32_e32 v248, v57, v248
	v_cvt_pk_bf16_f32 v224, v58, v59
	v_cvt_pk_bf16_f32 v225, v60, v61
	v_cvt_pk_bf16_f32 v226, v62, v63
	v_cvt_pk_bf16_f32 v227, v64, v65
	s_waitcnt lgkmcnt(2)
	s_nop 0
	v_mfma_f32_32x32x16_bf16 v[18:33], v[224:227], v[198:201], v[18:33]
	v_add_f32_e32 v245, v58, v245
	v_add_f32_e32 v246, v59, v246
	v_add_f32_e32 v247, v60, v247
	v_add_f32_e32 v248, v61, v248
	v_mfma_f32_32x32x16_bf16 v[2:17], v[224:227], v[212:215], v[2:17]
	ds_read_b128 v[198:201], v244 offset:24800
	ds_read_b128 v[212:215], v244 offset:33504
	v_add_f32_e32 v245, v62, v245
	v_add_f32_e32 v246, v63, v246
	v_add_f32_e32 v247, v64, v247
	v_add_f32_e32 v248, v65, v248
	v_cvt_pk_bf16_f32 v216, v34, v35
	v_cvt_pk_bf16_f32 v217, v36, v37
	v_cvt_pk_bf16_f32 v218, v38, v39
	v_cvt_pk_bf16_f32 v219, v40, v41
	s_waitcnt lgkmcnt(2)
	s_nop 0
	v_mfma_f32_32x32x16_bf16 v[18:33], v[216:219], v[190:193], v[18:33]
	v_add_f32_e32 v245, v34, v245
	v_add_f32_e32 v246, v35, v246
	v_add_f32_e32 v247, v36, v247
	v_add_f32_e32 v248, v37, v248
	v_mfma_f32_32x32x16_bf16 v[2:17], v[216:219], v[194:197], v[2:17]
	v_add_f32_e32 v245, v38, v245
	v_add_f32_e32 v246, v39, v246
	v_add_f32_e32 v247, v40, v247
	v_add_f32_e32 v248, v41, v248
	v_cvt_pk_bf16_f32 v224, v42, v43
	v_cvt_pk_bf16_f32 v225, v44, v45
	v_cvt_pk_bf16_f32 v226, v46, v47
	v_cvt_pk_bf16_f32 v227, v48, v49
	s_waitcnt lgkmcnt(0)
	s_nop 0
	v_mfma_f32_32x32x16_bf16 v[18:33], v[224:227], v[198:201], v[18:33]
	v_add_f32_e32 v245, v42, v245
	v_add_f32_e32 v246, v43, v246
	v_add_f32_e32 v247, v44, v247
	v_add_f32_e32 v248, v45, v248
	v_mfma_f32_32x32x16_bf16 v[2:17], v[224:227], v[212:215], v[2:17]
	v_add_f32_e32 v245, v46, v245
	v_add_f32_e32 v246, v47, v246
	v_add_f32_e32 v247, v48, v247
	v_add_f32_e32 v248, v49, v248
	v_add_f32_e32 v245, v245, v246
	v_add_f32_e32 v247, v247, v248
	v_add_f32_e32 v245, v245, v247
	s_nop 0
	v_add_f32_e32 v0, v0, v245
